# GEMM1 peeled last k-iteration: ks1 B fragments read early into spare registers, A fragments double-buffered with counted lgkmcnt
# baseline (speedup 1.0000x reference)
; #define G_WAIT_V0() asm volatile("s_waitcnt vmcnt(0)" ::: "memory")
; __device__ __forceinline__ void g_kloop(const u16* __restrict__ Ab, const u16* __restrict__ Bb, const int K, char* smem, ...
;     ...
;     const char* sa = smem + cur * G_STAGE_B;
;     const char* sb = sa + G_TILE_B;
; #pragma unroll
;     for (int ks = 0; ks < 2; ++ks) {
;       s16x8 At[8], Bf[4];
; #pragma unroll
;       for (int m = 0; m < 8; ++m) At[m] = *(const s16x8*)(sa + g_lds_byte(wr * 128 + m * 16 + fr, ks * 32 + fq * 8));
; #pragma unroll
;       for (int n = 0; n < 4; ++n) Bf[n] = *(const s16x8*)(sb + g_lds_byte(wc * 64 + n * 16 + fr, ks * 32 + fq * 8));
; #pragma unroll
;       for (int m = 0; m < 8; ++m)
; #pragma unroll
;         for (int n = 0; n < 4; ++n)
;           acc[m][n] = __builtin_amdgcn_mfma_f32_16x16x32_bf16(__builtin_bit_cast(bf16x8, Bf[n]), __builtin_bit_cast(bf16x8, At[m]), acc[m][n], 0, 0, 0);
;     }
;     G_WAIT_V0();
;     __syncthreads();
;   }
; __device__ void gemm1_phase(const Params& P, int layer, char* smem) {
;     ...
;     const int cw = u.pn * 256 + wc * 64;
;     const int row0 = u.pm * 256 + wr * 128 + fr;
;     char* wsm = smem + G_STAGE_B + wid * 8192;
;     const int rowb = u.pm * 256 + wr * 128;
;     const bool rope_q = cw < 1024;
;     const bool rope_k = (cw >= C_KV + 256 && cw < C_KV + 384) || (cw >= C_KV + 512 && cw < C_KV + 640);
;     const bool mixed = (cw == 5888);
;     if (cw >= INC) {
.LBB0_122:
	s_mov_b32 s1, 0x18000
	v_add3_u32 v96, v172, v170, s1
	ds_read_b128 v[146:149], v96
	ds_read_b128 v[158:161], v96 offset:1024
	v_add3_u32 v201, v171, v170, s36
	ds_read_b128 v[130:133], v201
	v_add3_u32 v203, v169, v191, s36
	v_add3_u32 v212, v168, v191, s36
	v_add3_u32 v213, v167, v191, s36
	v_add3_u32 v199, v199, v191, s36
	v_add3_u32 v197, v197, v191, s36
	s_waitcnt lgkmcnt(0)
	v_mfma_f32_16x16x32_bf16 v[204:207], v[146:149], v[130:133], v[4:7]
	ds_read_b128 v[208:211], v96 offset:6144
	v_add3_u32 v193, v193, v191, s36
	v_add3_u32 v191, v192, v191, s36
	ds_read_b128 v[4:7], v96 offset:2048
	s_movk_i32 s1, 0x2340
	s_waitcnt lgkmcnt(0)
	v_mfma_f32_16x16x32_bf16 v[182:185], v[4:7], v[130:133], v[114:117]
	s_nop 2
	ds_read_b128 v[114:117], v96 offset:4096
	v_mfma_f32_16x16x32_bf16 v[106:109], v[208:211], v[130:133], v[106:109]
	s_waitcnt lgkmcnt(0)
	v_mfma_f32_16x16x32_bf16 v[178:181], v[114:117], v[130:133], v[110:113]
	ds_read_b128 v[130:133], v203
	s_waitcnt lgkmcnt(0)
	v_mfma_f32_16x16x32_bf16 v[174:177], v[208:211], v[130:133], v[48:51]
	s_nop 2
	ds_read_b128 v[48:51], v212
	s_waitcnt lgkmcnt(0)
	v_mfma_f32_16x16x32_bf16 v[166:169], v[208:211], v[48:51], v[36:39]
	s_nop 2
	ds_read_b128 v[36:39], v213
	s_waitcnt lgkmcnt(0)
	v_mfma_f32_16x16x32_bf16 v[154:157], v[208:211], v[36:39], v[24:27]
	s_nop 2
	ds_read_b128 v[24:27], v199
	s_waitcnt lgkmcnt(0)
	v_mfma_f32_16x16x32_bf16 v[142:145], v[208:211], v[24:27], v[16:19]
	s_nop 2
	ds_read_b128 v[16:19], v197
	v_mfma_f32_16x16x32_bf16 v[110:113], v[4:7], v[130:133], v[92:95]
	v_mfma_f32_16x16x32_bf16 v[170:173], v[114:117], v[130:133], v[76:79]
	v_mfma_f32_16x16x32_bf16 v[92:95], v[146:149], v[48:51], v[98:101]
	v_mfma_f32_16x16x32_bf16 v[84:87], v[4:7], v[48:51], v[84:87]
	v_mfma_f32_16x16x32_bf16 v[162:165], v[114:117], v[48:51], v[64:67]
	v_mfma_f32_16x16x32_bf16 v[64:67], v[146:149], v[36:39], v[88:91]
	v_mfma_f32_16x16x32_bf16 v[76:79], v[4:7], v[36:39], v[72:75]
	v_mfma_f32_16x16x32_bf16 v[150:153], v[114:117], v[36:39], v[52:55]
	v_mfma_f32_16x16x32_bf16 v[48:51], v[146:149], v[24:27], v[80:83]
	v_mfma_f32_16x16x32_bf16 v[52:55], v[4:7], v[24:27], v[60:63]
	v_mfma_f32_16x16x32_bf16 v[40:43], v[114:117], v[24:27], v[40:43]
	s_waitcnt lgkmcnt(0)
	v_mfma_f32_16x16x32_bf16 v[24:27], v[146:149], v[16:19], v[68:71]
	v_mfma_f32_16x16x32_bf16 v[36:39], v[4:7], v[16:19], v[44:47]
	v_mfma_f32_16x16x32_bf16 v[44:47], v[114:117], v[16:19], v[28:31]
	v_mfma_f32_16x16x32_bf16 v[138:141], v[208:211], v[16:19], v[12:15]
	ds_read_b128 v[16:19], v193
	s_waitcnt lgkmcnt(0)
	v_mfma_f32_16x16x32_bf16 v[134:137], v[208:211], v[16:19], v[8:11]
	s_nop 2
	ds_read_b128 v[8:11], v191
	ds_read_b128 v[216:219], v96 offset:3072
	ds_read_b128 v[230:233], v96 offset:5120
	ds_read_b128 v[248:251], v96 offset:7168
	ds_read_b128 v[244:247], v201 offset:1024
	v_mfma_f32_16x16x32_bf16 v[102:105], v[146:149], v[130:133], v[102:105]
	v_mfma_f32_16x16x32_bf16 v[12:15], v[146:149], v[16:19], v[56:59]
	v_mfma_f32_16x16x32_bf16 v[28:31], v[4:7], v[16:19], v[32:35]
	v_mfma_f32_16x16x32_bf16 v[130:133], v[114:117], v[16:19], v[20:23]
	s_waitcnt lgkmcnt(4)
	v_mfma_f32_16x16x32_bf16 v[16:19], v[146:149], v[8:11], v[122:125]
	v_mfma_f32_16x16x32_bf16 v[146:149], v[208:211], v[8:11], v[0:3]
	s_nop 2
	ds_read_b128 v[0:3], v203 offset:1024
	v_mfma_f32_16x16x32_bf16 v[20:23], v[4:7], v[8:11], v[118:121]
	v_mfma_f32_16x16x32_bf16 v[4:7], v[114:117], v[8:11], v[126:129]
	s_waitcnt lgkmcnt(1)
	v_mfma_f32_16x16x32_bf16 v[114:117], v[158:161], v[244:247], v[204:207]
	v_mfma_f32_16x16x32_bf16 v[118:121], v[216:219], v[244:247], v[182:185]
	v_mfma_f32_16x16x32_bf16 v[126:129], v[230:233], v[244:247], v[178:181]
	v_mfma_f32_16x16x32_bf16 v[122:125], v[248:251], v[244:247], v[106:109]
	ds_read_b128 v[244:247], v212 offset:1024
	s_waitcnt lgkmcnt(1)
	v_mfma_f32_16x16x32_bf16 v[106:109], v[158:161], v[0:3], v[102:105]
	v_mfma_f32_16x16x32_bf16 v[98:101], v[216:219], v[0:3], v[110:113]
	v_mfma_f32_16x16x32_bf16 v[110:113], v[230:233], v[0:3], v[170:173]
	v_mfma_f32_16x16x32_bf16 v[102:105], v[248:251], v[0:3], v[174:177]
	ds_read_b128 v[0:3], v213 offset:1024
	s_waitcnt lgkmcnt(1)
	v_mfma_f32_16x16x32_bf16 v[88:91], v[158:161], v[244:247], v[92:95]
	v_mfma_f32_16x16x32_bf16 v[80:83], v[216:219], v[244:247], v[84:87]
	v_mfma_f32_16x16x32_bf16 v[92:95], v[230:233], v[244:247], v[162:165]
	v_mfma_f32_16x16x32_bf16 v[84:87], v[248:251], v[244:247], v[166:169]
	ds_read_b128 v[244:247], v199 offset:1024
	s_waitcnt lgkmcnt(1)
	v_mfma_f32_16x16x32_bf16 v[72:75], v[158:161], v[0:3], v[64:67]
	v_mfma_f32_16x16x32_bf16 v[64:67], v[216:219], v[0:3], v[76:79]
	v_mfma_f32_16x16x32_bf16 v[76:79], v[230:233], v[0:3], v[150:153]
	v_mfma_f32_16x16x32_bf16 v[68:71], v[248:251], v[0:3], v[154:157]
	ds_read_b128 v[0:3], v197 offset:1024
	s_waitcnt lgkmcnt(1)
	v_mfma_f32_16x16x32_bf16 v[56:59], v[158:161], v[244:247], v[48:51]
	v_mfma_f32_16x16x32_bf16 v[48:51], v[216:219], v[244:247], v[52:55]
	v_mfma_f32_16x16x32_bf16 v[60:63], v[230:233], v[244:247], v[40:43]
	v_mfma_f32_16x16x32_bf16 v[52:55], v[248:251], v[244:247], v[142:145]
	ds_read_b128 v[244:247], v193 offset:1024
	s_waitcnt lgkmcnt(1)
	v_mfma_f32_16x16x32_bf16 v[40:43], v[158:161], v[0:3], v[24:27]
	v_mfma_f32_16x16x32_bf16 v[32:35], v[216:219], v[0:3], v[36:39]
	v_mfma_f32_16x16x32_bf16 v[44:47], v[230:233], v[0:3], v[44:47]
	v_mfma_f32_16x16x32_bf16 v[36:39], v[248:251], v[0:3], v[138:141]
	ds_read_b128 v[212:215], v191 offset:1024
	s_waitcnt lgkmcnt(1)
	v_mfma_f32_16x16x32_bf16 v[24:27], v[158:161], v[244:247], v[12:15]
	v_mfma_f32_16x16x32_bf16 v[8:11], v[216:219], v[244:247], v[28:31]
	v_mfma_f32_16x16x32_bf16 v[28:31], v[230:233], v[244:247], v[130:133]
	v_mfma_f32_16x16x32_bf16 v[12:15], v[248:251], v[244:247], v[134:137]
	s_nop 1
	v_or_b32_e32 v130, s4, v190
	v_cmp_gt_i32_e32 vcc, s1, v130
	s_waitcnt lgkmcnt(0)
	v_mfma_f32_16x16x32_bf16 v[16:19], v[158:161], v[212:215], v[16:19]
	s_waitcnt vmcnt(0)
	s_waitcnt vmcnt(0)
	s_barrier
	v_mfma_f32_16x16x32_bf16 v[0:3], v[216:219], v[212:215], v[20:23]
	v_mfma_f32_16x16x32_bf16 v[20:23], v[230:233], v[212:215], v[4:7]
	v_mfma_f32_16x16x32_bf16 v[4:7], v[248:251], v[212:215], v[146:149]
	s_and_saveexec_b64 s[10:11], vcc
	v_readlane_b32 s26, v254, 52
	v_readlane_b32 s27, v254, 53
	s_cbranch_execz .LBB0_113
	v_lshlrev_b32_e32 v96, 7, v186
	v_add_u32_e32 v132, s0, v189
	v_and_b32_e32 v96, 0xffffe000, v96
	s_movk_i32 s0, 0x3ff
	v_or_b32_e32 v134, v132, v188
	v_add_u32_e32 v146, 0x10000, v96
	v_cmp_lt_i32_e64 s[4:5], s0, v130
	v_and_b32_e32 v136, 63, v186
	v_bfe_u32 v133, v186, 4, 2
	s_mov_b64 s[0:1], 0
	s_and_saveexec_b64 s[12:13], s[4:5]
	s_xor_b64 s[12:13], exec, s[12:13]
	s_cbranch_execz .LBB0_135
	v_and_b32_e32 v96, 0xffffff80, v130
	s_movk_i32 s0, 0x5ff
	v_cmp_lt_i32_e32 vcc, s0, v96
	s_mov_b64 s[16:17], 0
	s_mov_b64 s[14:15], 0
	s_and_saveexec_b64 s[0:1], vcc
	s_xor_b64 s[0:1], exec, s[0:1]
	s_cbranch_execnz .LBB0_127
	s_andn2_saveexec_b64 s[18:19], s[0:1]
	s_cbranch_execnz .LBB0_128

; __global__ void __launch_bounds__(NTHREADS, 2) mega_kernel(Params P) {
;   __shared__ __attribute__((aligned(1024))) char smem[163840];
amdhsa.kernels:
  - .agpr_count:     0
    .args:
      - .offset:         0
        .size:           312
        .value_kind:     by_value
      - .offset:         312
        .size:           4
        .value_kind:     hidden_block_count_x
      - .offset:         316
        .size:           4
        .value_kind:     hidden_block_count_y
      - .offset:         320
        .size:           4
        .value_kind:     hidden_block_count_z
      - .offset:         324
        .size:           2
        .value_kind:     hidden_group_size_x
      - .offset:         326
        .size:           2
        .value_kind:     hidden_group_size_y
      - .offset:         328
        .size:           2
        .value_kind:     hidden_group_size_z
      - .offset:         330
        .size:           2
        .value_kind:     hidden_remainder_x
      - .offset:         332
        .size:           2
        .value_kind:     hidden_remainder_y
      - .offset:         334
        .size:           2
        .value_kind:     hidden_remainder_z
      - .offset:         352
        .size:           8
        .value_kind:     hidden_global_offset_x
      - .offset:         360
        .size:           8
        .value_kind:     hidden_global_offset_y
      - .offset:         368
        .size:           8
        .value_kind:     hidden_global_offset_z
      - .offset:         376
        .size:           2
        .value_kind:     hidden_grid_dims
      - .offset:         400
        .size:           8
        .value_kind:     hidden_multigrid_sync_arg
    .group_segment_fixed_size: 163840
    .kernarg_segment_align: 8
    .kernarg_segment_size: 568
    .language:       OpenCL C
    .language_version:
      - 2
      - 0
    .max_flat_workgroup_size: 512
    .name:           _Z11mega_kernel6Params
    .private_segment_fixed_size: 0
    .sgpr_count:     108
    .sgpr_spill_count: 191
    .symbol:         _Z11mega_kernel6Params.kd
    .uniform_work_group_size: 1
    .uses_dynamic_stack: false
    .vgpr_count:     256
    .vgpr_spill_count: 0
    .wavefront_size: 64
